# mlstm_seq: gate loads and y stores 16 B per lane (v_permlane32_swap), half the vector-memory instructions
# speedup vs baseline: 1.0326x; 1.0191x over previous
; #define LAS __attribute__((address_space(3)))
; #define MFMA32(a, b, c) __builtin_amdgcn_mfma_f32_32x32x16_bf16((a), (b), (c), 0, 0, 0)
; __device__ __forceinline__ void mlstm_seq(LAS unsigned char* lds, int tid_in, int b, int h, const bf16_t* z1, const bf16_t* z2a, const float* g_hnorm, bf16_t* yb, const unsigned char* ws) {
;     ...
;     ML_PREFETCH(0);
; #pragma nounroll
;     for (int c = 0; c < 64; ++c) {
;         const size_t tok0 = (size_t)b * SEQL + c * 64;
;         const float decay = pdec;
; #pragma unroll
;         for (int i = 0; i < 2; ++i) { *(LAS u32x4*)(Qb + (srow + 32 * i) * QS + sc16 * 16) = pq[i]; *(LAS u32x4*)(KUb + (srow + 32 * i) * US + sc16 * 16) = pk[i]; }
; #pragma unroll
;         for (int i = 0; i < 4; ++i) *(LAS u32x4*)(Vb + (vrow + 16 * i) * VS + vc * 16) = pv[i];
;         *(LAS u32x4*)(SCb + (tid >> 3) * SS + (tid & 7) * 16) = psc;
;         u32x2 zo[2][4];
; #pragma unroll
;         for (int tb = 0; tb < 2; ++tb)
; #pragma unroll
;             for (int g = 0; g < 4; ++g) zo[tb][g] = pzo[tb][g];
;         const float wi0 = pwi0, wi1 = pwi1, wq = pwq, eq = peq, dq0 = pdq, dn = pdn;
;         __syncthreads();
;         if (c + 1 < 64) ML_PREFETCH(c + 1);
;     ...
;                     const LAS unsigned char* p = Qb + (32 * tb + r) * QS + (32 * dkb + 16 * s2 + 4 * hh) * 2;
;                     const u32x2 lo = *(const LAS u32x2*)p, hi = *(const LAS u32x2*)(p + 16);
;                     const u32x4 bq = {lo.x, lo.y, hi.x, hi.y};
;                     Z[tb] = MFMA32(ax, __builtin_bit_cast(bf16x8, bq), Z[tb]);
;                 }
;             }
;         { float f[16]; { float t8[8]; unpack8(*(const LAS u32x4*)(Qb + tq * QS + part * 32), t8);
; #pragma unroll
;               for (int e = 0; e < 8; ++e) f[e] = t8[e];
;               unpack8(*(const LAS u32x4*)(Qb + tq * QS + part * 32 + 16), t8);
; #pragma unroll
;               for (int e = 0; e < 8; ++e) f[8 + e] = t8[e]; }
;           float dq = 0.f;
; #pragma unroll
;           for (int j = 0; j < 4; ++j) { const f32x4 n4 = *(const LAS f32x4*)(NV + 16 * part + 4 * j); dq += (f[4 * j] * n4[0] + f[4 * j + 1] * n4[1]) + (f[4 * j + 2] * n4[2] + f[4 * j + 3] * n4[3]); }
.Lml_first:
	v_and_b32_e32 v136, 32, v220
	v_mov_b32_e32 v137, 0
	v_lshrrev_b32_e32 v136, 2, v136
	v_lshl_add_u64 v[150:151], v[150:151], 0, v[136:137]
	v_lshl_add_u64 v[168:169], v[168:169], 0, v[136:137]
	v_mov_b32_e32 v250, v134
	v_mov_b32_e32 v251, v135
	ds_write_b128 v0, v[98:101]
	ds_write_b128 v206, v[102:105] offset:17408
	ds_write_b128 v0, v[106:109] offset:8704
	ds_write_b128 v206, v[110:113] offset:27648
	ds_write_b128 v202, v[114:117] offset:37888
	ds_write_b128 v202, v[118:121] offset:47104
	ds_write_b128 v202, v[122:125] offset:56320
	ds_write_b128 v203, v[126:129] offset:27648
	ds_write_b128 v207, v[130:133]
	s_waitcnt lgkmcnt(0)
	s_barrier
.Lml_loop:
	v_add_u32_e32 v144, 0x2000, v208
	ds_read2_b64 v[146:149], v208 offset1:2
	ds_read2_b64 v[222:225], v144 offset0:64 offset1:66
	ds_read2_b64 v[230:233], v208 offset0:4 offset1:6
	ds_read2_b64 v[234:237], v144 offset0:68 offset1:70
	ds_read_b128 v[242:245], v209
	ds_read_b128 v[246:249], v209 offset:16
	ds_read_b128 v[238:241], v165
	s_cmp_eq_u32 s14, 1
	s_cbranch_scc1 .Lml_nopf
	v_lshl_add_u64 v[66:67], s[66:67], 0, v[176:177]
	v_add_co_u32_e32 v68, vcc, 0x6068000, v66
	s_add_u32 s12, s66, s8
	s_nop 0
	v_addc_co_u32_e32 v69, vcc, 0, v67, vcc
	global_load_dwordx4 v[98:101], v[68:69], off offset:2560
	v_add_co_u32_e32 v68, vcc, 0x6069000, v66
	s_addc_u32 s13, s67, s9
	s_nop 0
	v_addc_co_u32_e32 v69, vcc, 0, v67, vcc
	global_load_dwordx4 v[102:105], v[68:69], off offset:512
	v_add_co_u32_e32 v68, vcc, 0x609c000, v66
	global_load_dword v215, v1, s[12:13]
	s_nop 0
	v_addc_co_u32_e32 v69, vcc, 0, v67, vcc
	v_add_co_u32_e32 v66, vcc, 0x609d000, v66
	global_load_dwordx4 v[106:109], v[68:69], off offset:2560
	s_nop 0
	v_addc_co_u32_e32 v67, vcc, 0, v67, vcc
	global_load_dwordx4 v[110:113], v[66:67], off offset:512
	v_lshl_add_u64 v[66:67], s[66:67], 0, v[172:173]
	v_add_co_u32_e32 v68, vcc, 0x10880000, v66
	v_mov_b32_e32 v219, v216
	s_nop 0
	v_addc_co_u32_e32 v69, vcc, 0, v67, vcc
	global_load_dwordx4 v[114:117], v[68:69], off
	v_add_co_u32_e32 v68, vcc, 0x108a0000, v66
	s_nop 1
	v_addc_co_u32_e32 v69, vcc, 0, v67, vcc
	global_load_dwordx4 v[118:121], v[68:69], off
	v_add_co_u32_e32 v68, vcc, 0x108c0000, v66
	s_nop 1
	v_addc_co_u32_e32 v69, vcc, 0, v67, vcc
	v_add_co_u32_e32 v66, vcc, 0x108e0000, v66
	global_load_dwordx4 v[122:125], v[68:69], off
	s_nop 0
	v_addc_co_u32_e32 v67, vcc, 0, v67, vcc
	global_load_dwordx4 v[126:129], v[66:67], off
	v_lshl_add_u64 v[66:67], s[66:67], 0, v[162:163]
	global_load_dwordx4 v[130:133], v[66:67], off
	v_lshl_add_u64 v[66:67], s[66:67], 0, v[150:151]
	v_add_co_u32_e32 v68, vcc, 0x10881000, v66
	s_nop 1
	v_addc_co_u32_e32 v69, vcc, 0, v67, vcc
	v_add_co_u32_e32 v66, vcc, 0x108c1000, v66
	global_load_dwordx4 v[182:185], v[68:69], off
	global_load_dwordx4 v[186:189], v[68:69], off offset:32
	v_addc_co_u32_e32 v67, vcc, 0, v67, vcc
	global_load_dwordx4 v[190:193], v[66:67], off
	global_load_dwordx4 v[194:197], v[66:67], off offset:32
	v_lshl_add_u64 v[66:67], s[66:67], 0, v[170:171]
	v_add_co_u32_e32 v68, vcc, 0x1dc80000, v66
	s_nop 1
	v_addc_co_u32_e32 v69, vcc, 0, v67, vcc
	v_add_co_u32_e32 v66, vcc, 0x1de80000, v66
	global_load_dword v217, v[68:69], off offset:2048
	s_nop 0
	v_addc_co_u32_e32 v67, vcc, 0, v67, vcc
	global_load_dword v218, v[66:67], off offset:2048
	s_and_saveexec_b64 s[12:13], s[40:41]
	s_cbranch_execz .LBB0_86
	v_lshl_add_u64 v[66:67], s[66:67], 0, v[160:161]
	global_load_dword v219, v[66:67], off

; #define LAS __attribute__((address_space(3)))
; #define LDS_WAIT() asm volatile("s_waitcnt lgkmcnt(0)" ::: "memory")
; __device__ __forceinline__ void mlstm_seq(LAS unsigned char* lds, int tid_in, int b, int h, const bf16_t* z1, const bf16_t* z2a, const float* g_hnorm, bf16_t* yb, const unsigned char* ws) {
;     ...
;         for (int i = 0; i < 2; ++i) { *(LAS u32x4*)(Qb + (srow + 32 * i) * QS + sc16 * 16) = pq[i]; *(LAS u32x4*)(KUb + (srow + 32 * i) * US + sc16 * 16) = pk[i]; }
; #pragma unroll
;         for (int i = 0; i < 4; ++i) *(LAS u32x4*)(Vb + (vrow + 16 * i) * VS + vc * 16) = pv[i];
;         *(LAS u32x4*)(SCb + (tid >> 3) * SS + (tid & 7) * 16) = psc;
;     ...
;         LDS_WAIT(); __builtin_amdgcn_s_barrier(); asm volatile("" ::: "memory");
;         if (tid < 128) NV[tid] = decay * NV[tid] + dn;
.Lml_nvskip:
	s_or_b64 exec, exec, s[12:13]
	v_lshl_add_u64 v[134:135], s[66:67], 0, v[168:169]
	v_add_co_u32_e32 v136, vcc, s78, v134
	s_add_u32 s8, s8, 4
	s_addc_u32 s9, s9, 0
	v_addc_co_u32_e32 v137, vcc, 0, v135, vcc
	v_add_co_u32_e32 v138, vcc, s79, v134
	s_mov_b64 s[16:17], 0x800
	s_nop 0
	v_addc_co_u32_e32 v139, vcc, 0, v135, vcc
	s_waitcnt lgkmcnt(0)
	s_cmp_eq_u32 s14, 1
	s_cbranch_scc1 .Lml_nostage
	s_waitcnt vmcnt(6)
	ds_write_b128 v0, v[98:101]
	ds_write_b128 v206, v[102:105] offset:17408
	ds_write_b128 v0, v[106:109] offset:8704
	ds_write_b128 v206, v[110:113] offset:27648
	ds_write_b128 v202, v[114:117] offset:37888
	ds_write_b128 v202, v[118:121] offset:47104
	ds_write_b128 v202, v[122:125] offset:56320
	ds_write_b128 v203, v[126:129] offset:27648
	ds_write_b128 v207, v[130:133]
; #define LAS __attribute__((address_space(3)))
; __device__ __forceinline__ float bflo(unsigned w) { return __uint_as_float(w << 16); }
; __device__ __forceinline__ float bfhi(unsigned w) { return __uint_as_float(w & 0xffff0000u); }
; __device__ __forceinline__ unsigned pk2(float lo, float hi) { return pg8::cvt_pk_bf16(lo, hi); }
; __device__ __forceinline__ void mlstm_seq(LAS unsigned char* lds, int tid_in, int b, int h, const bf16_t* z1, const bf16_t* z2a, const float* g_hnorm, bf16_t* yb, const unsigned char* ws) {
;     ...
;         u32x2 zo[2][4];
; #pragma unroll
;         for (int tb = 0; tb < 2; ++tb)
; #pragma unroll
;             for (int g = 0; g < 4; ++g) zo[tb][g] = pzo[tb][g];
;         const float wi0 = pwi0, wi1 = pwi1, wq = pwq, eq = peq, dq0 = pdq, dn = pdn;
;     ...
; #pragma unroll
;         for (int tb = 0; tb < 2; ++tb) {
;             const int t = 32 * tb + r;
;             const float inv = INV[t];
;             const f32x4 pa = *(const LAS f32x4*)(PR + t * 8), pb = *(const LAS f32x4*)(PR + t * 8 + 4);
;             const float rn = inv * rsqrtf(inv * inv * ((pa[0] + pa[1]) + (pa[2] + pa[3]) + (pb[0] + pb[1]) + (pb[2] + pb[3])) * (1.f / 256.f) + EPSN);
; #pragma unroll
;             for (int g = 0; g < 4; ++g) {
;                 const int dv = 32 * wid + 8 * g + 4 * hh;
;                 u32x2 w; w.x = pk2(Z[tb][4 * g] * rn * bflo(zo[tb][g].x), Z[tb][4 * g + 1] * rn * bfhi(zo[tb][g].x));
;                 w.y = pk2(Z[tb][4 * g + 2] * rn * bflo(zo[tb][g].y), Z[tb][4 * g + 3] * rn * bfhi(zo[tb][g].y));
;                 *(u32x2*)(yb + (tok0 + t) * Z2_LD + h * 256 + dv) = w;
;             }
;         }
.Lml_nostage:
	s_mov_b64 s[12:13], 0x80000
	v_mul_f32_e32 v140, v226, v226
	v_add_f32_e32 v141, v223, v222
	v_add_f32_e32 v142, v224, v225
	v_add_f32_e32 v143, v232, v233
	v_add_f32_e32 v146, v230, v231
	v_add_f32_e32 v141, v141, v142
	v_add_f32_e32 v141, v141, v146
	v_add_f32_e32 v141, v143, v141
	v_mul_f32_e32 v141, v140, v141
	v_fmamk_f32 v141, v141, 0x3b800000, v221
	v_mul_f32_e32 v142, 0x4b800000, v141
	v_cmp_gt_f32_e32 vcc, s77, v141
	s_nop 1
	v_cndmask_b32_e32 v141, v141, v142, vcc
	v_rsq_f32_e32 v141, v141
	s_nop 0
	v_mul_f32_e32 v142, 0x45800000, v141
	v_cndmask_b32_e32 v141, v141, v142, vcc
	v_mul_f32_e32 v145, v226, v141
	v_mul_f32_e32 v82, v82, v145
	v_lshlrev_b32_e32 v140, 16, v180
	v_mul_f32_e32 v83, v83, v145
	v_and_b32_e32 v141, 0xffff0000, v180
	v_mul_f32_e32 v82, v82, v140
	v_mul_f32_e32 v83, v83, v141
	v_mul_f32_e32 v84, v84, v145
	v_lshlrev_b32_e32 v142, 16, v181
	v_mul_f32_e32 v85, v85, v145
	v_and_b32_e32 v143, 0xffff0000, v181
	v_mul_f32_e32 v84, v84, v142
	v_mul_f32_e32 v85, v85, v143
	v_mul_f32_e32 v86, v86, v145
	v_lshlrev_b32_e32 v140, 16, v178
	v_mul_f32_e32 v87, v87, v145
	v_and_b32_e32 v141, 0xffff0000, v178
	v_mul_f32_e32 v86, v86, v140
	v_mul_f32_e32 v87, v87, v141
	v_mul_f32_e32 v88, v88, v145
	v_lshlrev_b32_e32 v142, 16, v179
	v_mul_f32_e32 v89, v89, v145
	v_and_b32_e32 v143, 0xffff0000, v179
	v_mul_f32_e32 v88, v88, v142
	v_mul_f32_e32 v89, v89, v143
	v_cvt_pk_bf16_f32 v82, v82, v83
	v_cvt_pk_bf16_f32 v83, v84, v85
	v_cvt_pk_bf16_f32 v84, v86, v87
	v_cvt_pk_bf16_f32 v85, v88, v89
	s_nop 1
	v_permlane32_swap_b32_e32 v82, v84
	v_permlane32_swap_b32_e32 v83, v85
	global_store_dwordx4 v[136:137], v[82:85], off
	v_mul_f32_e32 v90, v90, v145
	v_lshlrev_b32_e32 v140, 16, v174
	v_mul_f32_e32 v91, v91, v145
	v_and_b32_e32 v141, 0xffff0000, v174
	v_mul_f32_e32 v90, v90, v140
	v_mul_f32_e32 v91, v91, v141
	v_mul_f32_e32 v92, v92, v145
	v_lshlrev_b32_e32 v142, 16, v175
	v_mul_f32_e32 v93, v93, v145
	v_and_b32_e32 v143, 0xffff0000, v175
	v_mul_f32_e32 v92, v92, v142
	v_mul_f32_e32 v93, v93, v143
	v_mul_f32_e32 v94, v94, v145
	v_lshlrev_b32_e32 v140, 16, v166
	v_mul_f32_e32 v95, v95, v145
	v_and_b32_e32 v141, 0xffff0000, v166
	v_mul_f32_e32 v94, v94, v140
	v_mul_f32_e32 v95, v95, v141
	v_mul_f32_e32 v96, v96, v145
	v_lshlrev_b32_e32 v142, 16, v167
	v_mul_f32_e32 v97, v97, v145
	v_and_b32_e32 v143, 0xffff0000, v167
	v_mul_f32_e32 v96, v96, v142
	v_mul_f32_e32 v97, v97, v143
	v_cvt_pk_bf16_f32 v90, v90, v91
	v_cvt_pk_bf16_f32 v91, v92, v93
	v_cvt_pk_bf16_f32 v92, v94, v95
	v_cvt_pk_bf16_f32 v93, v96, v97
	s_nop 1
	v_permlane32_swap_b32_e32 v90, v92
	v_permlane32_swap_b32_e32 v91, v93
	global_store_dwordx4 v[136:137], v[90:93], off offset:32
	v_lshl_add_u64 v[150:151], v[150:151], 0, s[12:13]
	v_lshl_add_u64 v[172:173], v[172:173], 0, s[12:13]
	v_lshl_add_u64 v[168:169], v[168:169], 0, s[12:13]
	s_mov_b64 s[12:13], 0x68000
	v_mul_f32_e32 v140, v227, v227
	v_add_f32_e32 v141, v235, v234
	v_add_f32_e32 v142, v236, v237
	v_add_f32_e32 v143, v248, v249
	v_add_f32_e32 v146, v246, v247
	v_add_f32_e32 v141, v141, v142
	v_add_f32_e32 v141, v141, v146
	v_add_f32_e32 v141, v143, v141
	v_mul_f32_e32 v141, v140, v141
	v_fmamk_f32 v141, v141, 0x3b800000, v221
	v_mul_f32_e32 v142, 0x4b800000, v141
	v_cmp_gt_f32_e32 vcc, s77, v141
	s_nop 1
	v_cndmask_b32_e32 v141, v141, v142, vcc
	v_rsq_f32_e32 v141, v141
	s_nop 0
	v_mul_f32_e32 v142, 0x45800000, v141
	v_cndmask_b32_e32 v141, v141, v142, vcc
	v_mul_f32_e32 v145, v227, v141
	v_mul_f32_e32 v66, v66, v145
	v_lshlrev_b32_e32 v140, 16, v158
	v_mul_f32_e32 v67, v67, v145
	v_and_b32_e32 v141, 0xffff0000, v158
	v_mul_f32_e32 v66, v66, v140
	v_mul_f32_e32 v67, v67, v141
	v_mul_f32_e32 v68, v68, v145
	v_lshlrev_b32_e32 v142, 16, v159
	v_mul_f32_e32 v69, v69, v145
	v_and_b32_e32 v143, 0xffff0000, v159
	v_mul_f32_e32 v68, v68, v142
	v_mul_f32_e32 v69, v69, v143
	v_mul_f32_e32 v70, v70, v145
	v_lshlrev_b32_e32 v140, 16, v156
	v_mul_f32_e32 v71, v71, v145
	v_and_b32_e32 v141, 0xffff0000, v156
	v_mul_f32_e32 v70, v70, v140
	v_mul_f32_e32 v71, v71, v141
	v_mul_f32_e32 v72, v72, v145
	v_lshlrev_b32_e32 v142, 16, v157
	v_mul_f32_e32 v73, v73, v145
	v_and_b32_e32 v143, 0xffff0000, v157
	v_mul_f32_e32 v72, v72, v142
	v_mul_f32_e32 v73, v73, v143
	v_cvt_pk_bf16_f32 v66, v66, v67
	v_cvt_pk_bf16_f32 v67, v68, v69
	v_cvt_pk_bf16_f32 v68, v70, v71
	v_cvt_pk_bf16_f32 v69, v72, v73
	s_nop 1
	v_permlane32_swap_b32_e32 v66, v68
	v_permlane32_swap_b32_e32 v67, v69
	global_store_dwordx4 v[138:139], v[66:69], off
	v_mul_f32_e32 v74, v74, v145
	v_lshlrev_b32_e32 v140, 16, v154
	v_mul_f32_e32 v75, v75, v145
	v_and_b32_e32 v141, 0xffff0000, v154
	v_mul_f32_e32 v74, v74, v140
	v_mul_f32_e32 v75, v75, v141
	v_mul_f32_e32 v76, v76, v145
	v_lshlrev_b32_e32 v142, 16, v155
	v_mul_f32_e32 v77, v77, v145
	v_and_b32_e32 v143, 0xffff0000, v155
	v_mul_f32_e32 v76, v76, v142
	v_mul_f32_e32 v77, v77, v143
	v_mul_f32_e32 v78, v78, v145
	v_lshlrev_b32_e32 v140, 16, v152
	v_mul_f32_e32 v79, v79, v145
	v_and_b32_e32 v141, 0xffff0000, v152
	v_mul_f32_e32 v78, v78, v140
	v_mul_f32_e32 v79, v79, v141
	v_mul_f32_e32 v80, v80, v145
	v_lshlrev_b32_e32 v142, 16, v153
	v_mul_f32_e32 v81, v81, v145
	v_and_b32_e32 v143, 0xffff0000, v153
	v_mul_f32_e32 v80, v80, v142
	v_mul_f32_e32 v81, v81, v143
	v_cvt_pk_bf16_f32 v74, v74, v75
	v_cvt_pk_bf16_f32 v75, v76, v77
	v_cvt_pk_bf16_f32 v76, v78, v79
	v_cvt_pk_bf16_f32 v77, v80, v81
	s_nop 1
	v_permlane32_swap_b32_e32 v74, v76
	v_permlane32_swap_b32_e32 v75, v77
	global_store_dwordx4 v[138:139], v[74:77], off offset:32
	v_lshl_add_u64 v[160:161], v[160:161], 0, s[92:93]
	v_lshl_add_u64 v[162:163], v[162:163], 0, s[94:95]
	v_lshl_add_u64 v[170:171], v[170:171], 0, s[16:17]
	v_lshl_add_u64 v[176:177], v[176:177], 0, s[12:13]
	s_add_i32 s14, s14, -1
	s_waitcnt vmcnt(4)
	v_permlane32_swap_b32_e32 v182, v184
	v_permlane32_swap_b32_e32 v183, v185
	v_permlane32_swap_b32_e32 v186, v188
	v_permlane32_swap_b32_e32 v187, v189
	v_permlane32_swap_b32_e32 v190, v192
	v_permlane32_swap_b32_e32 v191, v193
	v_permlane32_swap_b32_e32 v194, v196
	v_permlane32_swap_b32_e32 v195, v197
	v_mov_b64_e32 v[180:181], v[182:183]
	v_mov_b64_e32 v[178:179], v[184:185]
	v_mov_b64_e32 v[174:175], v[186:187]
	v_mov_b64_e32 v[166:167], v[188:189]
	v_mov_b64_e32 v[158:159], v[190:191]
	v_mov_b64_e32 v[156:157], v[192:193]
	v_mov_b64_e32 v[154:155], v[194:195]
	v_mov_b64_e32 v[152:153], v[196:197]
	v_mov_b32_e32 v250, v217
	v_mov_b32_e32 v251, v218
	v_mov_b32_e32 v216, v219
	v_mov_b32_e32 v164, v215
	s_cmp_eq_u32 s14, 0
	s_cbranch_scc1 .LBB0_93
	s_waitcnt lgkmcnt(0)
	s_barrier
	s_branch .Lml_loop
	s_nop 0
	s_nop 0
	s_nop 0
	s_nop 0
	s_nop 0
	s_nop 0
	s_nop 0
	s_nop 0
	s_nop 0
	s_nop 0
	s_nop 0
	s_nop 0
	s_nop 0
	s_nop 0
	s_nop 0
	s_nop 0
	s_nop 0
	s_nop 0
	s_nop 0
	s_nop 0
	s_nop 0
	s_nop 0
	s_nop 0
	s_nop 0
	s_nop 0
	s_nop 0
	s_nop 0
	s_nop 0
	s_nop 0
	s_nop 0
	s_nop 0
	s_nop 0
	s_nop 0
	s_nop 0
	s_nop 0
